# counted lgkmcnt waits at first consumer for the two QK fragment groups in the attention tile loop
# speedup vs baseline: 1.0121x; 1.0037x over previous
; #define LAS __attribute__((address_space(3)))
; __device__ __forceinline__ void at_tile(LAS unsigned char* Kb, LAS unsigned char* Vb, const LAS float* biasl, int r, int g, int k0, int qw0, int qrow, float cfar,
;                                         const bf16x8 (&qf)[2][2], float (&mrow)[2], f32x4 (&ol)[2], f32x4 (&o)[2][8], bool first) {
;     ...
;     const bool far = (qw0 - (k0 + 63)) >= 128;
;     const float cf = far ? cfar : 0.f;
;     const float ci0 = first ? cf : cf - mrow[0], ci1 = first ? cf : cf - mrow[1];
;     bf16x8 kfa[8], kfb[8];
; #pragma unroll
;     for (int kb = 0; kb < 4; ++kb)
; #pragma unroll
;         for (int ks = 0; ks < 2; ++ks) kfa[kb * 2 + ks] = *(const LAS bf16x8*)(Kb + (kb * 16 + r) * AT_KROW + (((ks * 4 + g) ^ r) * 16));
;     __builtin_amdgcn_sched_barrier(0);
; #pragma unroll
;     for (int kb = 0; kb < 4; ++kb)
; #pragma unroll
;         for (int ks = 0; ks < 2; ++ks) kfb[kb * 2 + ks] = *(const LAS bf16x8*)(Kb + (kb * 16 + r) * AT_KROW + (((8 + ks * 4 + g) ^ r) * 16));
;     __builtin_amdgcn_sched_barrier(0);
; #pragma unroll
;     for (int kb = 0; kb < 4; ++kb) s[0][kb] = __builtin_amdgcn_mfma_f32_16x16x32_bf16(kfa[kb * 2], qf[0][0], (f32x4){ci0, ci0, ci0, ci0}, 0, 0, 0);
; #pragma unroll
;     for (int kb = 0; kb < 4; ++kb) s[0][kb] = __builtin_amdgcn_mfma_f32_16x16x32_bf16(kfa[kb * 2 + 1], qf[0][1], s[0][kb], 0, 0, 0);
;     __builtin_amdgcn_sched_barrier(0);
;     bf16x8 vf[16];
; #pragma unroll
;     for (int db = 0; db < 4; ++db)
; #pragma unroll
;         for (int kk = 0; kk < 2; ++kk) vf[db * 2 + kk] = *(const LAS bf16x8*)(Vb + (db * 16 + r) * AT_VROW + (((kk * 4 + g) ^ (r >> 1)) * 16));
;     __builtin_amdgcn_sched_barrier(0);
; #pragma unroll
;     for (int kb = 0; kb < 4; ++kb) s[1][kb] = __builtin_amdgcn_mfma_f32_16x16x32_bf16(kfb[kb * 2], qf[1][0], (f32x4){ci1, ci1, ci1, ci1}, 0, 0, 0);
; #pragma unroll
;     for (int kb = 0; kb < 4; ++kb) s[1][kb] = __builtin_amdgcn_mfma_f32_16x16x32_bf16(kfb[kb * 2 + 1], qf[1][1], s[1][kb], 0, 0, 0);
;     __builtin_amdgcn_sched_barrier(0);
.LBB0_1348:
	s_sub_i32 s9, s18, 64
	s_cmp_gt_i32 s9, s25
	s_cbranch_scc1 .LBB0_1356
	s_lshl_b32 s8, s8, 14
	v_add_u32_e32 v2, s8, v238
	v_add_u32_e32 v112, v2, v239
	v_add_u32_e32 v120, v2, v240
	ds_read_b128 v[92:95], v112
	ds_read_b128 v[96:99], v112 offset:4096
	ds_read_b128 v[100:103], v120
	ds_read_b128 v[104:107], v120 offset:4096
	ds_read_b128 v[108:111], v112 offset:8192
	ds_read_b128 v[112:115], v112 offset:12288
	ds_read_b128 v[116:119], v120 offset:8192
	ds_read_b128 v[120:123], v120 offset:12288
	s_cmpk_gt_i32 s31, 0x7f
	s_cselect_b64 vcc, -1, 0
	v_add_u32_e32 v125, v2, v241
	v_add_u32_e32 v2, v2, v242
	ds_read_b128 v[132:135], v125
	ds_read_b128 v[136:139], v125 offset:4096
	ds_read_b128 v[156:159], v2
	ds_read_b128 v[160:163], v2 offset:4096
	ds_read_b128 v[164:167], v125 offset:8192
	ds_read_b128 v[168:171], v125 offset:12288
	ds_read_b128 v[172:175], v2 offset:8192
	ds_read_b128 v[176:179], v2 offset:12288
	s_waitcnt lgkmcnt(8)
	v_mfma_f32_16x16x32_bf16 v[92:95], v[92:95], v[52:55], v[248:251]
	v_mfma_f32_16x16x32_bf16 v[96:99], v[96:99], v[52:55], v[248:251]
	v_mfma_f32_16x16x32_bf16 v[108:111], v[108:111], v[52:55], v[248:251]
	v_mfma_f32_16x16x32_bf16 v[112:115], v[112:115], v[52:55], v[248:251]
	v_mfma_f32_16x16x32_bf16 v[152:155], v[100:103], v[56:59], v[92:95]
	v_mfma_f32_16x16x32_bf16 v[148:151], v[104:107], v[56:59], v[96:99]
	v_mfma_f32_16x16x32_bf16 v[144:147], v[116:119], v[56:59], v[108:111]
	v_mfma_f32_16x16x32_bf16 v[140:143], v[120:123], v[56:59], v[112:115]
	v_add_u32_e32 v2, s8, v243
	v_add_u32_e32 v181, v2, v244
	v_add_u32_e32 v180, v2, v245
	ds_read_b128 v[108:111], v181 offset:49152
	ds_read_b128 v[112:115], v181 offset:51200
	ds_read_b128 v[92:95], v180 offset:49152
	ds_read_b128 v[96:99], v180 offset:51200
	ds_read_b128 v[116:119], v181 offset:53248
	ds_read_b128 v[120:123], v181 offset:55296
	ds_read_b128 v[100:103], v180 offset:53248
	ds_read_b128 v[104:107], v180 offset:55296
	s_waitcnt lgkmcnt(8)
	v_mfma_f32_16x16x32_bf16 v[124:127], v[132:135], v[60:63], v[214:217]
	v_mfma_f32_16x16x32_bf16 v[132:135], v[136:139], v[60:63], v[214:217]
	v_mfma_f32_16x16x32_bf16 v[164:167], v[164:167], v[60:63], v[214:217]
	v_mfma_f32_16x16x32_bf16 v[168:171], v[168:171], v[60:63], v[214:217]
	v_mfma_f32_16x16x32_bf16 v[136:139], v[156:159], v[64:67], v[124:127]
	v_mfma_f32_16x16x32_bf16 v[132:135], v[160:163], v[64:67], v[132:135]
	v_mfma_f32_16x16x32_bf16 v[128:131], v[172:175], v[64:67], v[164:167]
	v_mfma_f32_16x16x32_bf16 v[124:127], v[176:179], v[64:67], v[168:171]
	s_and_b64 vcc, exec, vcc
	s_cbranch_vccnz .LBB0_1353
; __device__ __forceinline__ void at_tile(LAS unsigned char* Kb, LAS unsigned char* Vb, const LAS float* biasl, int r, int g, int k0, int qw0, int qrow, float cfar,
;                                         const bf16x8 (&qf)[2][2], float (&mrow)[2], f32x4 (&ol)[2], f32x4 (&o)[2][8], bool first) {
;     ...
;     if (!far) {
;         float badd[4][4];
; #pragma unroll
;         for (int kb = 0; kb < 4; ++kb)
; #pragma unroll
;             for (int j = 0; j < 4; ++j) { const int key = k0 + (kb >> 1) * 32 + g * 8 + (kb & 1) * 4 + j, dist = qrow - key;
;                 const int idx = dist < 0 ? 0 : (dist > 128 ? 128 : dist);
;                 badd[kb][j] = biasl[idx]; }
; #pragma unroll
;         for (int kb = 0; kb < 4; ++kb)
; #pragma unroll
;             for (int j = 0; j < 4; ++j) { const int key = k0 + (kb >> 1) * 32 + g * 8 + (kb & 1) * 4 + j;
;                 const float ad = (qrow >= key) ? badd[kb][j] : -INFINITY;
;                 s[0][kb][j] += ad; s[1][kb][j] += ad; }
;     }
	v_add_u32_e32 v162, s18, v202
	v_add_u32_e32 v165, s31, v246
	v_subrev_u32_e32 v2, 64, v162
	v_add_u32_e32 v156, 62, v165
	v_med3_i32 v156, v156, 0, v229
	s_add_i32 s8, 0, 0x18000
	v_or_b32_e32 v160, 2, v2
	v_lshl_add_u32 v159, v156, 2, s8
	v_sub_u32_e32 v156, v204, v160
	v_or_b32_e32 v163, 3, v2
	v_med3_i32 v156, v156, 0, v229
	v_lshl_add_u32 v164, v156, 2, s8
	v_sub_u32_e32 v156, v204, v163
	v_med3_i32 v156, v156, 0, v229
	v_lshl_add_u32 v166, v156, 2, s8
	v_or_b32_e32 v156, 4, v2
	v_sub_u32_e32 v158, v204, v156
	v_or_b32_e32 v157, 5, v2
	v_med3_i32 v158, v158, 0, v229
	v_lshl_add_u32 v167, v158, 2, s8
	v_sub_u32_e32 v158, v204, v157
	v_med3_i32 v158, v158, 0, v229
	v_lshl_add_u32 v168, v158, 2, s8
	v_or_b32_e32 v158, 6, v2
	v_or_b32_e32 v161, 7, v2
	v_sub_u32_e32 v169, v204, v158
	v_med3_i32 v169, v169, 0, v229
	v_sub_u32_e32 v170, v204, v161
	v_add_u32_e32 v171, 31, v165
	v_lshl_add_u32 v169, v169, 2, s8
	v_med3_i32 v170, v170, 0, v229
	v_med3_i32 v171, v171, 0, v229
	v_lshl_add_u32 v170, v170, 2, s8
	v_lshl_add_u32 v171, v171, 2, s8
	ds_read_b32 v179, v159
	ds_read_b32 v178, v164
	ds_read_b32 v182, v166
	ds_read_b32 v174, v167
	ds_read_b32 v176, v168
	ds_read_b32 v172, v169
	ds_read_b32 v175, v170
	ds_read_b32 v169, v171
	v_add_u32_e32 v168, 26, v165
	v_med3_i32 v168, v168, 0, v229
	v_lshl_add_u32 v170, v168, 2, s8
	v_add_u32_e32 v168, 25, v165
	v_xad_u32 v159, v2, s36, v204
	v_add_u32_e32 v166, 28, v165
	v_add_u32_e32 v167, 27, v165
	v_med3_i32 v168, v168, 0, v229
	v_med3_i32 v159, v159, 0, v229
	v_add_u32_e32 v164, 29, v165
	v_med3_i32 v166, v166, 0, v229
	v_med3_i32 v167, v167, 0, v229
	v_lshl_add_u32 v183, v168, 2, s8
	v_add_u32_e32 v168, 24, v165
	v_lshl_add_u32 v159, v159, 2, s8
	v_med3_i32 v164, v164, 0, v229
	v_lshl_add_u32 v166, v166, 2, s8
	v_lshl_add_u32 v167, v167, 2, s8
	v_med3_i32 v168, v168, 0, v229
	v_lshl_add_u32 v164, v164, 2, s8
	v_lshl_add_u32 v184, v168, 2, s8
	ds_read_b32 v177, v159
	ds_read_b32 v171, v164
	ds_read_b32 v173, v166
	ds_read_b32 v168, v167
	ds_read_b32 v170, v170
	ds_read_b32 v166, v183
	ds_read_b32 v167, v184
	v_mov_b32_e32 v159, v2
	v_cmp_ge_i32_e32 vcc, v204, v2
	v_mov_b32_e32 v164, 0xff800000
	s_and_saveexec_b64 s[8:9], vcc
	v_add_u32_e32 v164, 63, v165
	v_med3_i32 v164, v164, 0, v229
	v_lshl_add_u32 v164, v164, 2, 0
	v_add_u32_e32 v164, 0x18000, v164
	ds_read_b32 v164, v164
	s_or_b64 exec, exec, s[8:9]
	v_cmp_gt_i32_e32 vcc, v204, v2
	v_subrev_u32_e32 v183, 32, v162
	s_waitcnt lgkmcnt(0)
	v_cndmask_b32_e32 v165, v230, v179, vcc
	v_cmp_ge_i32_e32 vcc, v3, v163
	v_pk_add_f32 v[152:153], v[152:153], v[164:165]
	v_pk_add_f32 v[136:137], v[136:137], v[164:165]
	v_cndmask_b32_e32 v179, v230, v182, vcc
	v_cmp_ge_i32_e32 vcc, v204, v160
	s_nop 1
	v_cndmask_b32_e32 v178, v230, v178, vcc
	v_cmp_ge_i32_e32 vcc, v3, v157
	v_pk_add_f32 v[154:155], v[154:155], v[178:179]
	v_pk_add_f32 v[138:139], v[138:139], v[178:179]
	v_cndmask_b32_e32 v157, v230, v176, vcc
	v_cmp_ge_i32_e32 vcc, v204, v156
	s_nop 1
	v_cndmask_b32_e32 v156, v230, v174, vcc
	v_cmp_ge_i32_e32 vcc, v3, v161
	v_pk_add_f32 v[148:149], v[148:149], v[156:157]
	v_pk_add_f32 v[132:133], v[132:133], v[156:157]
	v_cndmask_b32_e32 v161, v230, v175, vcc
	v_cmp_ge_i32_e32 vcc, v204, v158
	v_subrev_u32_e32 v156, 31, v162
	v_or_b32_e32 v158, 35, v159
	v_cndmask_b32_e32 v160, v230, v172, vcc
	v_cmp_ge_i32_e32 vcc, v3, v156
	v_pk_add_f32 v[150:151], v[150:151], v[160:161]
	v_pk_add_f32 v[134:135], v[134:135], v[160:161]
	v_cndmask_b32_e32 v157, v230, v177, vcc
	v_cmp_ge_i32_e32 vcc, v204, v183
	v_or_b32_e32 v160, 34, v2
	s_nop 0
	v_cndmask_b32_e32 v156, v230, v169, vcc
	v_cmp_ge_i32_e32 vcc, v3, v158
	v_pk_add_f32 v[144:145], v[144:145], v[156:157]
	v_pk_add_f32 v[128:129], v[128:129], v[156:157]
	v_cndmask_b32_e32 v161, v230, v173, vcc
	v_cmp_ge_i32_e32 vcc, v204, v160
	v_or_b32_e32 v156, 37, v159
	v_or_b32_e32 v158, 36, v2
	v_cndmask_b32_e32 v160, v230, v171, vcc
	v_cmp_ge_i32_e32 vcc, v3, v156
	v_or_b32_e32 v2, 38, v2
	v_pk_add_f32 v[146:147], v[146:147], v[160:161]
	v_cndmask_b32_e32 v157, v230, v170, vcc
	v_cmp_ge_i32_e32 vcc, v204, v158
	v_or_b32_e32 v158, 39, v159
	v_pk_add_f32 v[130:131], v[130:131], v[160:161]
	v_cndmask_b32_e32 v156, v230, v168, vcc
	v_cmp_ge_i32_e32 vcc, v3, v158
	v_pk_add_f32 v[140:141], v[140:141], v[156:157]
	v_pk_add_f32 v[124:125], v[124:125], v[156:157]
	v_cndmask_b32_e32 v159, v230, v167, vcc
	v_cmp_ge_i32_e32 vcc, v204, v2
	s_nop 1
	v_cndmask_b32_e32 v158, v230, v166, vcc
	v_pk_add_f32 v[142:143], v[142:143], v[158:159]
	v_pk_add_f32 v[126:127], v[126:127], v[158:159]

; #define LAS __attribute__((address_space(3)))
; __device__ __forceinline__ void at_tile(LAS unsigned char* Kb, LAS unsigned char* Vb, const LAS float* biasl, int r, int g, int k0, int qw0, int qrow, float cfar,
;                                         const bf16x8 (&qf)[2][2], float (&mrow)[2], f32x4 (&ol)[2], f32x4 (&o)[2][8], bool first) {
;     ...
;     const bool far = (qw0 - (k0 + 63)) >= 128;
;     const float cf = far ? cfar : 0.f;
;     const float ci0 = first ? cf : cf - mrow[0], ci1 = first ? cf : cf - mrow[1];
;     bf16x8 kfa[8], kfb[8];
; #pragma unroll
;     for (int kb = 0; kb < 4; ++kb)
; #pragma unroll
;         for (int ks = 0; ks < 2; ++ks) kfa[kb * 2 + ks] = *(const LAS bf16x8*)(Kb + (kb * 16 + r) * AT_KROW + (((ks * 4 + g) ^ r) * 16));
;     __builtin_amdgcn_sched_barrier(0);
; #pragma unroll
;     for (int kb = 0; kb < 4; ++kb)
; #pragma unroll
;         for (int ks = 0; ks < 2; ++ks) kfb[kb * 2 + ks] = *(const LAS bf16x8*)(Kb + (kb * 16 + r) * AT_KROW + (((8 + ks * 4 + g) ^ r) * 16));
;     __builtin_amdgcn_sched_barrier(0);
; #pragma unroll
;     for (int kb = 0; kb < 4; ++kb) s[0][kb] = __builtin_amdgcn_mfma_f32_16x16x32_bf16(kfa[kb * 2], qf[0][0], (f32x4){ci0, ci0, ci0, ci0}, 0, 0, 0);
; #pragma unroll
;     for (int kb = 0; kb < 4; ++kb) s[0][kb] = __builtin_amdgcn_mfma_f32_16x16x32_bf16(kfa[kb * 2 + 1], qf[0][1], s[0][kb], 0, 0, 0);
;     __builtin_amdgcn_sched_barrier(0);
;     bf16x8 vf[16];
; #pragma unroll
;     for (int db = 0; db < 4; ++db)
; #pragma unroll
;         for (int kk = 0; kk < 2; ++kk) vf[db * 2 + kk] = *(const LAS bf16x8*)(Vb + (db * 16 + r) * AT_VROW + (((kk * 4 + g) ^ (r >> 1)) * 16));
;     __builtin_amdgcn_sched_barrier(0);
; #pragma unroll
;     for (int kb = 0; kb < 4; ++kb) s[1][kb] = __builtin_amdgcn_mfma_f32_16x16x32_bf16(kfb[kb * 2], qf[1][0], (f32x4){ci1, ci1, ci1, ci1}, 0, 0, 0);
; #pragma unroll
;     for (int kb = 0; kb < 4; ++kb) s[1][kb] = __builtin_amdgcn_mfma_f32_16x16x32_bf16(kfb[kb * 2 + 1], qf[1][1], s[1][kb], 0, 0, 0);
;     __builtin_amdgcn_sched_barrier(0);
.LBB0_1373:
	s_sub_i32 s9, s18, 64
	s_cmp_gt_i32 s9, s5
	s_cbranch_scc1 .LBB0_1381
	s_lshl_b32 s8, s8, 14
	v_add_u32_e32 v2, s8, v238
	v_add_u32_e32 v112, v2, v239
	v_add_u32_e32 v120, v2, v240
	ds_read_b128 v[92:95], v112
	ds_read_b128 v[96:99], v112 offset:4096
	ds_read_b128 v[100:103], v120
	ds_read_b128 v[104:107], v120 offset:4096
	ds_read_b128 v[108:111], v112 offset:8192
	ds_read_b128 v[112:115], v112 offset:12288
	ds_read_b128 v[116:119], v120 offset:8192
	ds_read_b128 v[120:123], v120 offset:12288
	s_cmpk_gt_i32 s21, 0x7f
	s_cselect_b64 vcc, -1, 0
	v_add_u32_e32 v125, v2, v241
	v_add_u32_e32 v2, v2, v242
	ds_read_b128 v[132:135], v125
	ds_read_b128 v[136:139], v125 offset:4096
	ds_read_b128 v[156:159], v2
	ds_read_b128 v[160:163], v2 offset:4096
	ds_read_b128 v[164:167], v125 offset:8192
	ds_read_b128 v[168:171], v125 offset:12288
	ds_read_b128 v[172:175], v2 offset:8192
	ds_read_b128 v[176:179], v2 offset:12288
	s_waitcnt lgkmcnt(8)
	v_mfma_f32_16x16x32_bf16 v[92:95], v[92:95], v[56:59], v[248:251]
	v_mfma_f32_16x16x32_bf16 v[96:99], v[96:99], v[56:59], v[248:251]
	v_mfma_f32_16x16x32_bf16 v[108:111], v[108:111], v[56:59], v[248:251]
	v_mfma_f32_16x16x32_bf16 v[112:115], v[112:115], v[56:59], v[248:251]
	v_mfma_f32_16x16x32_bf16 v[152:155], v[100:103], v[60:63], v[92:95]
	v_mfma_f32_16x16x32_bf16 v[148:151], v[104:107], v[60:63], v[96:99]
	v_mfma_f32_16x16x32_bf16 v[144:147], v[116:119], v[60:63], v[108:111]
	v_mfma_f32_16x16x32_bf16 v[140:143], v[120:123], v[60:63], v[112:115]
	v_add_u32_e32 v2, s8, v243
	v_add_u32_e32 v181, v2, v244
	v_add_u32_e32 v180, v2, v245
	ds_read_b128 v[108:111], v181 offset:49152
	ds_read_b128 v[112:115], v181 offset:51200
	ds_read_b128 v[92:95], v180 offset:49152
	ds_read_b128 v[96:99], v180 offset:51200
	ds_read_b128 v[116:119], v181 offset:53248
	ds_read_b128 v[120:123], v181 offset:55296
	ds_read_b128 v[100:103], v180 offset:53248
	ds_read_b128 v[104:107], v180 offset:55296
	s_waitcnt lgkmcnt(8)
	v_mfma_f32_16x16x32_bf16 v[124:127], v[132:135], v[64:67], v[214:217]
	v_mfma_f32_16x16x32_bf16 v[132:135], v[136:139], v[64:67], v[214:217]
	v_mfma_f32_16x16x32_bf16 v[164:167], v[164:167], v[64:67], v[214:217]
	v_mfma_f32_16x16x32_bf16 v[168:171], v[168:171], v[64:67], v[214:217]
	v_mfma_f32_16x16x32_bf16 v[136:139], v[156:159], v[68:71], v[124:127]
	v_mfma_f32_16x16x32_bf16 v[132:135], v[160:163], v[68:71], v[132:135]
	v_mfma_f32_16x16x32_bf16 v[128:131], v[172:175], v[68:71], v[164:167]
	v_mfma_f32_16x16x32_bf16 v[124:127], v[176:179], v[68:71], v[168:171]
	s_and_b64 vcc, exec, vcc
	s_cbranch_vccnz .LBB0_1378
; __device__ __forceinline__ void at_tile(LAS unsigned char* Kb, LAS unsigned char* Vb, const LAS float* biasl, int r, int g, int k0, int qw0, int qrow, float cfar,
;                                         const bf16x8 (&qf)[2][2], float (&mrow)[2], f32x4 (&ol)[2], f32x4 (&o)[2][8], bool first) {
;     ...
;     if (!far) {
;         float badd[4][4];
; #pragma unroll
;         for (int kb = 0; kb < 4; ++kb)
; #pragma unroll
;             for (int j = 0; j < 4; ++j) { const int key = k0 + (kb >> 1) * 32 + g * 8 + (kb & 1) * 4 + j, dist = qrow - key;
;                 const int idx = dist < 0 ? 0 : (dist > 128 ? 128 : dist);
;                 badd[kb][j] = biasl[idx]; }
; #pragma unroll
;         for (int kb = 0; kb < 4; ++kb)
; #pragma unroll
;             for (int j = 0; j < 4; ++j) { const int key = k0 + (kb >> 1) * 32 + g * 8 + (kb & 1) * 4 + j;
;                 const float ad = (qrow >= key) ? badd[kb][j] : -INFINITY;
;                 s[0][kb][j] += ad; s[1][kb][j] += ad; }
;     }
	v_add_u32_e32 v162, s18, v202
	v_add_u32_e32 v165, s21, v246
	v_subrev_u32_e32 v2, 64, v162
	v_add_u32_e32 v156, 62, v165
	v_med3_i32 v156, v156, 0, v229
	s_add_i32 s8, 0, 0x18000
	v_or_b32_e32 v160, 2, v2
	v_lshl_add_u32 v159, v156, 2, s8
	v_sub_u32_e32 v156, v204, v160
	v_or_b32_e32 v163, 3, v2
	v_med3_i32 v156, v156, 0, v229
	v_lshl_add_u32 v164, v156, 2, s8
	v_sub_u32_e32 v156, v204, v163
	v_med3_i32 v156, v156, 0, v229
	v_lshl_add_u32 v166, v156, 2, s8
	v_or_b32_e32 v156, 4, v2
	v_sub_u32_e32 v158, v204, v156
	v_or_b32_e32 v157, 5, v2
	v_med3_i32 v158, v158, 0, v229
	v_lshl_add_u32 v167, v158, 2, s8
	v_sub_u32_e32 v158, v204, v157
	v_med3_i32 v158, v158, 0, v229
	v_lshl_add_u32 v168, v158, 2, s8
	v_or_b32_e32 v158, 6, v2
	v_or_b32_e32 v161, 7, v2
	v_sub_u32_e32 v169, v204, v158
	v_med3_i32 v169, v169, 0, v229
	v_sub_u32_e32 v170, v204, v161
	v_add_u32_e32 v171, 31, v165
	v_lshl_add_u32 v169, v169, 2, s8
	v_med3_i32 v170, v170, 0, v229
	v_med3_i32 v171, v171, 0, v229
	v_lshl_add_u32 v170, v170, 2, s8
	v_lshl_add_u32 v171, v171, 2, s8
	ds_read_b32 v179, v159
	ds_read_b32 v178, v164
	ds_read_b32 v182, v166
	ds_read_b32 v174, v167
	ds_read_b32 v176, v168
	ds_read_b32 v172, v169
	ds_read_b32 v175, v170
	ds_read_b32 v169, v171
	v_add_u32_e32 v168, 26, v165
	v_med3_i32 v168, v168, 0, v229
	v_lshl_add_u32 v170, v168, 2, s8
	v_add_u32_e32 v168, 25, v165
	v_xad_u32 v159, v2, s36, v204
	v_add_u32_e32 v166, 28, v165
	v_add_u32_e32 v167, 27, v165
	v_med3_i32 v168, v168, 0, v229
	v_med3_i32 v159, v159, 0, v229
	v_add_u32_e32 v164, 29, v165
	v_med3_i32 v166, v166, 0, v229
	v_med3_i32 v167, v167, 0, v229
	v_lshl_add_u32 v183, v168, 2, s8
	v_add_u32_e32 v168, 24, v165
	v_lshl_add_u32 v159, v159, 2, s8
	v_med3_i32 v164, v164, 0, v229
	v_lshl_add_u32 v166, v166, 2, s8
	v_lshl_add_u32 v167, v167, 2, s8
	v_med3_i32 v168, v168, 0, v229
	v_lshl_add_u32 v164, v164, 2, s8
	v_lshl_add_u32 v184, v168, 2, s8
	ds_read_b32 v177, v159
	ds_read_b32 v171, v164
	ds_read_b32 v173, v166
	ds_read_b32 v168, v167
	ds_read_b32 v170, v170
	ds_read_b32 v166, v183
	ds_read_b32 v167, v184
	v_mov_b32_e32 v159, v2
	v_cmp_ge_i32_e32 vcc, v204, v2
	v_mov_b32_e32 v164, 0xff800000
	s_and_saveexec_b64 s[8:9], vcc
	v_add_u32_e32 v164, 63, v165
	v_med3_i32 v164, v164, 0, v229
	v_lshl_add_u32 v164, v164, 2, 0
	v_add_u32_e32 v164, 0x18000, v164
	ds_read_b32 v164, v164
	s_or_b64 exec, exec, s[8:9]
	v_cmp_gt_i32_e32 vcc, v204, v2
	v_subrev_u32_e32 v183, 32, v162
	s_waitcnt lgkmcnt(0)
	v_cndmask_b32_e32 v165, v230, v179, vcc
	v_cmp_ge_i32_e32 vcc, v3, v163
	v_pk_add_f32 v[152:153], v[152:153], v[164:165]
	v_pk_add_f32 v[136:137], v[136:137], v[164:165]
	v_cndmask_b32_e32 v179, v230, v182, vcc
	v_cmp_ge_i32_e32 vcc, v204, v160
	s_nop 1
	v_cndmask_b32_e32 v178, v230, v178, vcc
	v_cmp_ge_i32_e32 vcc, v3, v157
	v_pk_add_f32 v[154:155], v[154:155], v[178:179]
	v_pk_add_f32 v[138:139], v[138:139], v[178:179]
	v_cndmask_b32_e32 v157, v230, v176, vcc
	v_cmp_ge_i32_e32 vcc, v204, v156
	s_nop 1
	v_cndmask_b32_e32 v156, v230, v174, vcc
	v_cmp_ge_i32_e32 vcc, v3, v161
	v_pk_add_f32 v[148:149], v[148:149], v[156:157]
	v_pk_add_f32 v[132:133], v[132:133], v[156:157]
	v_cndmask_b32_e32 v161, v230, v175, vcc
	v_cmp_ge_i32_e32 vcc, v204, v158
	v_subrev_u32_e32 v156, 31, v162
	v_or_b32_e32 v158, 35, v159
	v_cndmask_b32_e32 v160, v230, v172, vcc
	v_cmp_ge_i32_e32 vcc, v3, v156
	v_pk_add_f32 v[150:151], v[150:151], v[160:161]
	v_pk_add_f32 v[134:135], v[134:135], v[160:161]
	v_cndmask_b32_e32 v157, v230, v177, vcc
	v_cmp_ge_i32_e32 vcc, v204, v183
	v_or_b32_e32 v160, 34, v2
	s_nop 0
	v_cndmask_b32_e32 v156, v230, v169, vcc
	v_cmp_ge_i32_e32 vcc, v3, v158
	v_pk_add_f32 v[144:145], v[144:145], v[156:157]
	v_pk_add_f32 v[128:129], v[128:129], v[156:157]
	v_cndmask_b32_e32 v161, v230, v173, vcc
	v_cmp_ge_i32_e32 vcc, v204, v160
	v_or_b32_e32 v156, 37, v159
	v_or_b32_e32 v158, 36, v2
	v_cndmask_b32_e32 v160, v230, v171, vcc
	v_cmp_ge_i32_e32 vcc, v3, v156
	v_or_b32_e32 v2, 38, v2
	v_pk_add_f32 v[146:147], v[146:147], v[160:161]
	v_cndmask_b32_e32 v157, v230, v170, vcc
	v_cmp_ge_i32_e32 vcc, v204, v158
	v_or_b32_e32 v158, 39, v159
	v_pk_add_f32 v[130:131], v[130:131], v[160:161]
	v_cndmask_b32_e32 v156, v230, v168, vcc
	v_cmp_ge_i32_e32 vcc, v3, v158
	v_pk_add_f32 v[140:141], v[140:141], v[156:157]
	v_pk_add_f32 v[124:125], v[124:125], v[156:157]
	v_cndmask_b32_e32 v159, v230, v167, vcc
	v_cmp_ge_i32_e32 vcc, v204, v2
	s_nop 1
	v_cndmask_b32_e32 v158, v230, v166, vcc
	v_pk_add_f32 v[142:143], v[142:143], v[158:159]
	v_pk_add_f32 v[126:127], v[126:127], v[158:159]
